# final-LayerNorm row loads (residual f32, gated bf16 output) marked nt as well: read-once streams
# baseline (speedup 1.0000x reference)
; DI void phase_lnf(const Params& p, int l, int tid) {
;     ...
;   if (row < R) { const float* src = lnf_res(p, l, row); const u16* os = p.G + (size_t)row * 1024;
; #pragma unroll
;     for (int j = 0; j < 4; j++) { v[j] = *(const float4*)(src + 4 * (lane + 64 * j)); ov[j] = *(const uint2*)(os + 4 * (lane + 64 * j)); } }
.LBB0_1301:
	s_or_b64 exec, exec, s[4:5]
	v_lshlrev_b32_e32 v0, 2, v0
	v_ashrrev_i32_e32 v47, 31, v46
	v_readlane_b32 s6, v253, 48
	v_and_b32_e32 v36, 0xfc, v0
	v_lshlrev_b64 v[4:5], 11, v[46:47]
	v_readlane_b32 s7, v253, 49
	v_lshlrev_b32_e32 v6, 2, v36
	v_mov_b32_e32 v7, v1
	v_lshl_add_u64 v[4:5], s[6:7], 0, v[4:5]
	v_lshlrev_b32_e32 v0, 1, v36
	v_lshl_add_u64 v[2:3], v[2:3], 0, v[6:7]
	v_lshl_add_u64 v[4:5], v[4:5], 0, v[0:1]
	global_load_dwordx4 v[18:21], v[2:3], off offset:3072 nt
	global_load_dwordx4 v[22:25], v[2:3], off offset:2048 nt
	global_load_dwordx2 v[64:65], v[4:5], off offset:1536 nt
	global_load_dwordx2 v[66:67], v[4:5], off offset:1024 nt
	global_load_dwordx2 v[68:69], v[4:5], off offset:512 nt
	global_load_dwordx2 v[70:71], v[4:5], off nt
	global_load_dwordx4 v[26:29], v[2:3], off offset:1024 nt
	global_load_dwordx4 v[30:33], v[2:3], off nt
	v_readlane_b32 s2, v254, 19
	v_readlane_b32 s3, v254, 20
	s_lshl_b32 s94, s2, 10
	v_readlane_b32 s52, v252, 32
	s_lshl_b64 s[2:3], s[94:95], 2
	v_readlane_b32 s66, v252, 46
	v_readlane_b32 s67, v252, 47
	s_add_u32 s4, s66, s2
	s_addc_u32 s5, s67, s3
	s_add_u32 s2, s36, s2
	v_or_b32_e32 v2, 0x300, v36
	v_or_b32_e32 v4, 0x200, v36
	v_or_b32_e32 v8, 0x100, v36
	s_addc_u32 s3, s37, s3
	v_lshl_add_u64 v[38:39], s[4:5], 0, v[6:7]
	v_lshl_add_u64 v[40:41], s[2:3], 0, v[6:7]
	v_lshl_add_u64 v[42:43], s[6:7], 0, v[0:1]
	v_lshl_add_u64 v[44:45], s[96:97], 0, v[0:1]
	s_mov_b64 s[10:11], 0
	v_lshlrev_b32_e32 v48, 2, v8
	v_lshlrev_b32_e32 v50, 2, v4
	v_lshlrev_b32_e32 v52, 2, v2
	v_readlane_b32 s53, v252, 33
	v_readlane_b32 s54, v252, 34
	v_readlane_b32 s55, v252, 35
	v_readlane_b32 s56, v252, 36
	v_readlane_b32 s57, v252, 37
	v_readlane_b32 s58, v252, 38
	v_readlane_b32 s59, v252, 39
	v_readlane_b32 s60, v252, 40
	v_readlane_b32 s61, v252, 41
	v_readlane_b32 s62, v252, 42
	v_readlane_b32 s63, v252, 43
	v_readlane_b32 s64, v252, 44
	v_readlane_b32 s65, v252, 45
	s_branch .LBB0_1303

; DI const float* lnf_res(const Params& p, int l, int row) {
;   const int b = row / SEQA, pos = row % SEQA;
;   if (pos < CTXL) return p.ctx + ((size_t)b * CTXL + pos) * 1024;
;   return (l == 0 ? p.x : (const float*)p.out) + ((size_t)b * SEQ + pos - CTXL) * 1024;
; }
; DI void phase_lnf(const Params& p, int l, int tid) {
;     ...
;     const int nrow = row + stride;
;     if (nrow < R) { const float* nsrc = lnf_res(p, l, nrow); const u16* nos = p.G + (size_t)nrow * 1024;
; #pragma unroll
;       for (int j = 0; j < 4; j++) { nv[j] = *(const float4*)(nsrc + 4 * (lane + 64 * j)); nov[j] = *(const uint2*)(nos + 4 * (lane + 64 * j)); } }
.LBB0_1303:
	v_add_u32_e32 v54, s19, v46
	s_mov_b32 s2, 0x87ff
	v_cmp_gt_i32_e64 s[4:5], s18, v54
	v_cmp_lt_i32_e32 vcc, s2, v54
	s_and_saveexec_b64 s[6:7], s[4:5]
	s_cbranch_execz .LBB0_1309
	s_mov_b32 s2, 0x78787879
	v_mul_hi_i32 v0, v54, s2
	v_lshrrev_b32_e32 v2, 31, v0
	v_ashrrev_i32_e32 v0, 11, v0
	v_add_u32_e32 v6, v0, v2
	v_mul_i32_i24_e32 v0, 0x1100, v6
	v_sub_u32_e32 v2, v54, v0
	s_movk_i32 s2, 0xff
	v_cmp_lt_i32_e64 s[4:5], s2, v2
	v_ashrrev_i32_e32 v7, 31, v6
	s_and_saveexec_b64 s[2:3], s[4:5]
	s_xor_b64 s[4:5], exec, s[2:3]
	v_mov_b32_e32 v3, v1
	v_lshlrev_b64 v[4:5], 24, v[6:7]
	v_lshl_add_u64 v[4:5], v[34:35], 0, v[4:5]
	v_lshlrev_b64 v[2:3], 12, v[2:3]
	v_lshl_add_u64 v[2:3], v[4:5], 0, v[2:3]
	v_lshl_add_u64 v[4:5], v[2:3], 0, s[20:21]
	s_andn2_saveexec_b64 s[4:5], s[4:5]
	v_ashrrev_i32_e32 v3, 31, v2
	v_lshlrev_b64 v[4:5], 20, v[6:7]
	v_lshl_add_u64 v[4:5], s[44:45], 0, v[4:5]
	v_lshlrev_b64 v[2:3], 12, v[2:3]
	v_lshl_add_u64 v[4:5], v[4:5], 0, v[2:3]
	s_or_b64 exec, exec, s[4:5]
	v_ashrrev_i32_e32 v55, 31, v54
	v_lshlrev_b64 v[2:3], 11, v[54:55]
	v_lshlrev_b32_e32 v0, 2, v36
	v_lshl_add_u64 v[14:15], v[4:5], 0, v[0:1]
	v_lshl_add_u64 v[62:63], v[42:43], 0, v[2:3]
	global_load_dwordx4 v[2:5], v[14:15], off nt
	global_load_dwordx4 v[6:9], v[14:15], off offset:1024 nt
	global_load_dwordx4 v[10:13], v[14:15], off offset:2048 nt
	s_nop 0
	global_load_dwordx4 v[14:17], v[14:15], off offset:3072 nt
	s_nop 0
	global_load_dwordx2 v[56:57], v[62:63], off nt
	global_load_dwordx2 v[58:59], v[62:63], off offset:512 nt
	global_load_dwordx2 v[60:61], v[62:63], off offset:1024 nt
	s_nop 0
	global_load_dwordx2 v[62:63], v[62:63], off offset:1536 nt
